# one-time stagger: blocks >= 256 sleep about half a loop period at the start of the GEMM and attention phases so the two co-resident blocks of a CU do not run their MFMA segments in lockstep
# speedup vs baseline: 1.0783x; 1.0145x over previous
; DI int xcc_id() { return (int)(__builtin_amdgcn_s_getreg((3 << 11) | 20) & 7u); }
; __global__ void __launch_bounds__(256, 2) mega(P p) {
;     ...
;       } else if (k == 6 && EN(7)) {
;         Epi e{};
;         e.xin_ctx = (l == 0) ? p.in[I_CTX] : (const float*)(ws + WS_X);
;         e.xin_lat = (l == 0) ? p.in[I_X] : (const float*)(ws + WS_X) + (size_t)NCTX * DM;
;         e.xout = (float*)(ws + WS_X); e.out = p.out;
;         e.gate_lat = modl + 4096; e.gate_ctx = modl + 6144 + 4096; e.last = (l == NL - 1);
;         const bf16_t* Bt = (const bf16_t*)(ws + WS_WTOUT) + (size_t)l * DM * LDP;
;         const int g0 = xcc_id();
;         for (int gi = 0; gi < 8; ++gi) {
;           const int g = (g0 + gi) & 7;
;           unsigned* gctr = ctrs + 128 + ph2 * 8 + g;
;           int tm, tn;
;           const int mt_n = e.last ? 64 : 66, mt_0 = e.last ? 2 : 0;
;           int i = next_item(gctr, &s_item);
.LBB0_10:
	v_readlane_b32 s0, v255, 11
	s_cmp_lt_i32 s0, 5
	s_mov_b64 s[0:1], -1
	s_cbranch_scc1 .LBB0_50
	v_readlane_b32 s0, v255, 11
	s_cmp_lt_i32 s0, 6
	s_mov_b64 s[0:1], -1
	s_cbranch_scc1 .LBB0_38
	v_readlane_b32 s0, v255, 11
	s_cmp_eq_u32 s0, 6
	v_readlane_b32 s0, v255, 2
	s_mov_b32 s16, s0
	v_readlane_b32 s24, v255, 3
	s_cbranch_scc0 .LBB0_37
	v_readlane_b32 s0, v252, 0
	s_nop 0
	s_cmpk_lt_u32 s0, 0x100
	s_cbranch_scc1 .Lstag_k6
	s_sleep 25
.Lstag_k6:
	v_readlane_b32 s1, v255, 4
	s_add_i32 s0, s1, 5
	v_readlane_b32 s16, v252, 12
	s_cmp_lt_u32 s0, 13
	v_readlane_b32 s17, v252, 13
	v_readlane_b32 s25, v252, 21
	v_readlane_b32 s0, v252, 49
	v_readlane_b32 s26, v252, 22
	v_readlane_b32 s10, v252, 46
	s_cselect_b32 s25, s17, s0
	v_readlane_b32 s0, v252, 48
	v_readlane_b32 s20, v252, 16
	v_readlane_b32 s21, v252, 17
	v_readlane_b32 s22, v252, 18
	v_readlane_b32 s23, v252, 19
	v_readlane_b32 s11, v252, 47
	s_cselect_b32 s26, s16, s0
	v_readlane_b32 s16, v255, 7
	v_readlane_b32 s27, v252, 23
	s_cselect_b32 s22, s21, s11
	s_cselect_b32 s23, s20, s10
	s_sub_i32 s2, s1, 22
	s_mul_i32 s1, s16, 0x840000
	v_readlane_b32 s3, v252, 50
	v_readlane_b32 s28, v252, 24
	s_mul_hi_i32 s0, s16, 0x840000
	s_add_u32 s27, s3, s1
	v_readlane_b32 s1, v252, 51
	s_addc_u32 s28, s1, s0
	s_lshl_b32 s0, s49, 3
	s_ashr_i32 s1, s0, 31
	v_readlane_b32 s29, v252, 25
	s_lshl_b64 s[0:1], s[0:1], 2
	s_add_u32 s29, s94, s0
	s_addc_u32 s36, s95, s1
	s_cmp_lt_u32 s2, 7
	s_cselect_b64 s[2:3], -1, 0
	s_and_b64 s[0:1], s[2:3], exec
	s_cselect_b32 s0, 64, 0x42
	s_cselect_b32 s37, 2, 0
	s_cselect_b32 s38, s92, s10
	s_cselect_b32 s39, s93, s11
	s_lshl_b32 s40, s0, 3
	v_cvt_f32_u32_e32 v0, s40
	s_lshl_b32 s43, s0, 4
	s_sub_i32 s0, 0, s40
	v_readlane_b32 s24, v252, 20
	v_rcp_iflag_f32_e32 v0, v0
	s_getreg_b32 s41, hwreg(HW_REG_XCC_ID, 0, 4)
	s_mov_b32 s42, 0
	v_readlane_b32 s24, v255, 3
	v_mul_f32_e32 v0, 0x4f7ffffe, v0
	v_cvt_u32_f32_e32 v0, v0
	v_readlane_b32 s18, v252, 14
	v_readlane_b32 s19, v252, 15
	v_readlane_b32 s30, v252, 26
	v_readfirstlane_b32 s1, v0
	s_mul_i32 s0, s0, s1
	s_mul_hi_u32 s0, s1, s0
	s_add_i32 s44, s1, s0
	v_readlane_b32 s0, v255, 2
	s_mov_b32 s16, s0
	v_readlane_b32 s31, v252, 27
	v_readlane_b32 s17, v255, 8
	s_branch .LBB0_15

; DI int xcc_id() { return (int)(__builtin_amdgcn_s_getreg((3 << 11) | 20) & 7u); }
; __global__ void __launch_bounds__(256, 2) mega(P p) {
;     ...
;       } else if (k == 4 && EN(5)) {
;         const int g0 = xcc_id();
;         for (int gi = 0; gi < 8; ++gi) {
;         const int g = (g0 + gi) & 7;
;         unsigned* gctr = ctrs + 128 + ph2 * 8 + g;
;         const int tot = (g < 4) ? 84 : 24 + 128;
;         for (int iq = next_item(gctr, &s_item); iq < tot; iq = next_item(gctr, &s_item)) {
.LBB0_50:
	s_andn2_b64 vcc, exec, s[0:1]
	s_cbranch_vccnz .LBB0_289
	v_readlane_b32 s0, v255, 11
	s_cmp_gt_i32 s0, 3
	s_mov_b64 s[0:1], -1
	s_cbranch_scc0 .LBB0_172
	v_readlane_b32 s0, v252, 0
	s_nop 0
	s_cmpk_lt_u32 s0, 0x100
	s_cbranch_scc1 .Lstag_k4
	s_sleep 34
.Lstag_k4:
	s_lshl_b32 s0, s49, 3
	s_ashr_i32 s1, s0, 31
	s_lshl_b64 s[0:1], s[0:1], 2
	s_getreg_b32 s86, hwreg(HW_REG_XCC_ID, 0, 4)
	s_add_u32 s87, s94, s0
	s_addc_u32 s88, s95, s1
	s_mov_b32 s47, 0
	s_mov_b32 s48, s86
	v_writelane_b32 v255, s49, 12
	s_branch .LBB0_54

; DI int xcc_id() { return (int)(__builtin_amdgcn_s_getreg((3 << 11) | 20) & 7u); }
; __global__ void __launch_bounds__(256, 2) mega(P p) {
;     ...
;       } else if (k == 1 && EN(2)) {
;         Epi e{}; e.cb = U; e.cf = (float*)(ws + WS_AB);
;         const bf16_t* Bt = (const bf16_t*)(ws + WS_WTIN) + (size_t)l * INP * LDP;
;         const int g0 = xcc_id();
;         for (int gi = 0; gi < 8; ++gi) {
;           const int g = (g0 + gi) & 7;
;           unsigned* gctr = ctrs + 128 + ph2 * 8 + g;
;           int tm, tn;
;           int i = next_item(gctr, &s_item);
.LBB0_382:
	s_andn2_b64 vcc, exec, s[0:1]
	v_readlane_b32 s0, v255, 0
	s_mov_b32 s2, s0
	v_readlane_b32 s0, v255, 1
	s_mov_b32 s10, s0
	s_cbranch_vccnz .LBB0_472
	v_readlane_b32 s0, v252, 0
	s_nop 0
	s_cmpk_lt_u32 s0, 0x100
	s_cbranch_scc1 .Lstag_k1
	s_sleep 25
.Lstag_k1:
	v_readlane_b32 s0, v255, 7
	v_readlane_b32 s1, v255, 8
	s_mov_b32 s2, s0
	s_mul_i32 s1, s2, 0x17b8000
	v_readlane_b32 s2, v253, 52
	s_mul_hi_i32 s0, s0, 0x17b8000
	s_add_u32 s22, s2, s1
	v_readlane_b32 s1, v253, 53
	s_addc_u32 s23, s1, s0
	s_lshl_b32 s0, s49, 3
	s_ashr_i32 s1, s0, 31
	s_lshl_b64 s[0:1], s[0:1], 2
	s_add_u32 s25, s94, s0
	v_readlane_b32 s0, v255, 0
	s_mov_b32 s2, s0
	v_readlane_b32 s0, v255, 1
	s_getreg_b32 s24, hwreg(HW_REG_XCC_ID, 0, 4)
	s_addc_u32 s26, s95, s1
	s_mov_b32 s27, 0
	s_mov_b32 s10, s0
	s_branch .LBB0_385
